# GEMM tile heads: accumulator zeroing interleaved 1:1 with the scalar next-tile index arithmetic (two waves per SIMD overlap SALU and VALU); loop-head byte phases kept
# speedup vs baseline: 1.0028x; 1.0028x over previous
.Lzskip_gin:
	v_mov_b64_e32 v[18:19], 0
	v_mov_b64_e32 v[20:21], 0
	v_mov_b64_e32 v[22:23], 0
	v_mov_b64_e32 v[24:25], 0
	v_mov_b64_e32 v[26:27], 0
	v_mov_b64_e32 v[28:29], 0
	v_mov_b64_e32 v[30:31], 0
	v_mov_b64_e32 v[32:33], 0
	v_mov_b64_e32 v[34:35], 0
	v_mov_b64_e32 v[36:37], 0
	v_mov_b64_e32 v[38:39], 0
	v_mov_b64_e32 v[40:41], 0
	v_mov_b64_e32 v[42:43], 0
	v_mov_b64_e32 v[44:45], 0
	v_mov_b64_e32 v[46:47], 0
	v_mov_b64_e32 v[48:49], 0
	v_mov_b64_e32 v[50:51], 0
	v_mov_b64_e32 v[52:53], 0
	v_mov_b64_e32 v[54:55], 0
	v_mov_b64_e32 v[56:57], 0
	v_mov_b64_e32 v[58:59], 0
	v_mov_b64_e32 v[60:61], 0
	v_mov_b64_e32 v[62:63], 0
	v_mov_b64_e32 v[64:65], 0
	v_mov_b64_e32 v[66:67], 0
	v_mov_b64_e32 v[68:69], 0
	v_mov_b64_e32 v[70:71], 0
	v_mov_b64_e32 v[72:73], 0
	v_mov_b64_e32 v[74:75], 0
	v_mov_b64_e32 v[76:77], 0
	v_mov_b64_e32 v[78:79], 0
	v_mov_b64_e32 v[80:81], 0
	v_mov_b64_e32 v[82:83], 0
	v_mov_b64_e32 v[84:85], 0
	v_mov_b64_e32 v[86:87], 0
	v_mov_b64_e32 v[88:89], 0
	v_mov_b64_e32 v[90:91], 0
	v_mov_b64_e32 v[92:93], 0
	v_mov_b64_e32 v[94:95], 0
	v_mov_b64_e32 v[96:97], 0
	v_mov_b64_e32 v[98:99], 0
	v_mov_b64_e32 v[100:101], 0
	v_mov_b64_e32 v[102:103], 0
	v_mov_b64_e32 v[104:105], 0
	v_mov_b64_e32 v[106:107], 0
	v_mov_b64_e32 v[108:109], 0
	v_mov_b64_e32 v[110:111], 0
	v_mov_b64_e32 v[112:113], 0
	v_mov_b64_e32 v[114:115], 0
	s_branch .LBB0_74
	s_nop 0
	s_nop 0
	s_nop 0
	s_nop 0
	s_nop 0
	s_nop 0
	s_nop 0
	s_nop 0
	s_nop 0
	s_nop 0
	s_nop 0
	s_nop 0
	s_nop 0
	s_nop 0

.LBB0_72:
	s_add_i32 s81, s81, 1
	v_mov_b64_e32 v[4:5], 0
	s_mul_i32 s2, s81, s48
	v_mov_b64_e32 v[6:7], 0
	s_mul_hi_u32 s6, s81, s12
	v_mov_b64_e32 v[8:9], 0
	s_add_i32 s6, s6, s2
	v_mov_b64_e32 v[10:11], 0
	s_mul_i32 s2, s81, s12
	v_mov_b64_e32 v[12:13], 0
	s_add_u32 s76, s2, s28
	v_mov_b64_e32 v[14:15], 0
	s_addc_u32 s77, s6, s17
	v_mov_b64_e32 v[16:17], 0
	v_mov_b64_e32 v[2:3], 0x600
	v_cmp_lt_i64_e64 s[38:39], s[76:77], v[2:3]
	v_mov_b64_e32 v[2:3], 0x5ff
	v_cmp_gt_i64_e32 vcc, s[76:77], v[2:3]
	s_cbranch_vccnz .Lzskip_gin
	s_ashr_i32 s2, s76, 31
	v_mov_b64_e32 v[18:19], 0
	s_lshr_b32 s2, s2, 29
	v_mov_b64_e32 v[20:21], 0
	s_add_i32 s2, s76, s2
	v_mov_b64_e32 v[22:23], 0
	s_ashr_i32 s6, s2, 3
	v_mov_b64_e32 v[24:25], 0
	s_and_b32 s2, s2, -8
	v_mov_b64_e32 v[26:27], 0
	s_sub_i32 s2, s76, s2
	v_mov_b64_e32 v[28:29], 0
	s_cmp_lt_i32 s2, 0
	v_mov_b64_e32 v[30:31], 0
	s_cselect_b32 s50, s72, 0xc0
	v_mov_b64_e32 v[32:33], 0
	s_mul_i32 s2, s2, s50
	v_mov_b64_e32 v[34:35], 0
	s_add_i32 s2, s2, s6
	v_mov_b64_e32 v[36:37], 0
	s_mul_hi_i32 s6, s2, 0x2aaaaaab
	v_mov_b64_e32 v[38:39], 0
	s_lshr_b32 s50, s6, 31
	v_mov_b64_e32 v[40:41], 0
	s_ashr_i32 s6, s6, 4
	v_mov_b64_e32 v[42:43], 0
	s_add_i32 s6, s6, s50
	v_mov_b64_e32 v[44:45], 0
	s_lshl_b32 s51, s6, 3
	v_mov_b64_e32 v[46:47], 0
	s_sub_i32 s50, 0x80, s51
	v_mov_b64_e32 v[48:49], 0
	s_min_i32 s62, s50, 8
	v_mov_b64_e32 v[50:51], 0
	s_abs_i32 s50, s62
	v_mov_b64_e32 v[52:53], 0
	v_cvt_f32_u32_e32 v2, s50
	v_mov_b64_e32 v[54:55], 0
	s_sub_i32 s68, 0, s50
	v_mov_b64_e32 v[56:57], 0
	s_mulk_i32 s6, 0x60
	v_mov_b64_e32 v[58:59], 0
	s_sub_i32 s2, s2, s6
	v_mov_b64_e32 v[60:61], 0
	v_rcp_iflag_f32_e32 v2, v2
	v_mov_b64_e32 v[62:63], 0
	s_abs_i32 s6, s2
	v_mov_b64_e32 v[64:65], 0
	s_xor_b32 s63, s2, s62
	v_mov_b64_e32 v[66:67], 0
	s_ashr_i32 s63, s63, 31
	v_mov_b64_e32 v[68:69], 0
	v_mul_f32_e32 v2, 0x4f7ffffe, v2
	v_mov_b64_e32 v[70:71], 0
	v_cvt_u32_f32_e32 v2, v2
	v_mov_b64_e32 v[72:73], 0
	s_nop 0
	v_mov_b64_e32 v[74:75], 0
	v_readfirstlane_b32 s69, v2
	v_mov_b64_e32 v[76:77], 0
	s_mul_i32 s68, s68, s69
	v_mov_b64_e32 v[78:79], 0
	s_mul_hi_u32 s68, s69, s68
	v_mov_b64_e32 v[80:81], 0
	s_add_i32 s69, s69, s68
	v_mov_b64_e32 v[82:83], 0
	s_mul_hi_u32 s68, s6, s69
	v_mov_b64_e32 v[84:85], 0
	s_mul_i32 s69, s68, s50
	v_mov_b64_e32 v[86:87], 0
	s_sub_i32 s6, s6, s69
	v_mov_b64_e32 v[88:89], 0
	s_add_i32 s70, s68, 1
	v_mov_b64_e32 v[90:91], 0
	s_sub_i32 s69, s6, s50
	v_mov_b64_e32 v[92:93], 0
	s_cmp_ge_u32 s6, s50
	v_mov_b64_e32 v[94:95], 0
	s_cselect_b32 s68, s70, s68
	v_mov_b64_e32 v[96:97], 0
	s_cselect_b32 s6, s69, s6
	v_mov_b64_e32 v[98:99], 0
	s_add_i32 s69, s68, 1
	v_mov_b64_e32 v[100:101], 0
	s_cmp_ge_u32 s6, s50
	v_mov_b64_e32 v[102:103], 0
	s_cselect_b32 s6, s69, s68
	v_mov_b64_e32 v[104:105], 0
	s_xor_b32 s6, s6, s63
	v_mov_b64_e32 v[106:107], 0
	s_sub_i32 s50, s6, s63
	v_mov_b64_e32 v[108:109], 0
	s_mul_i32 s6, s50, s62
	v_mov_b64_e32 v[110:111], 0
	s_sub_i32 s2, s2, s6
	v_mov_b64_e32 v[112:113], 0
	s_add_i32 s62, s51, s2
	v_mov_b64_e32 v[114:115], 0
.LBB0_74:
	s_ashr_i32 s63, s62, 31
	v_mov_b64_e32 v[116:117], 0
	s_lshl_b64 s[68:69], s[62:63], 19
	v_mov_b64_e32 v[118:119], 0
	s_add_u32 s76, s36, s68
	v_mov_b64_e32 v[120:121], 0
	s_addc_u32 s77, s37, s69
	v_mov_b64_e32 v[122:123], 0
	s_and_b64 s[68:69], s[38:39], exec
	v_mov_b64_e32 v[124:125], 0
	s_cselect_b32 s2, s77, s91
	v_mov_b64_e32 v[126:127], 0
	s_cselect_b32 s6, s76, s90
	v_mov_b64_e32 v[128:129], 0
	s_ashr_i32 s51, s50, 31
	s_lshl_b64 s[68:69], s[50:51], 19
	s_add_u32 s78, s42, s68
	s_addc_u32 s79, s43, s69
	s_and_b64 s[68:69], s[38:39], exec
	s_cselect_b32 s51, s79, s93
	s_cselect_b32 s63, s78, s92
	s_add_u32 s90, s90, 0x40080
	s_addc_u32 s91, s91, 0
	s_add_u32 s89, s92, 0x100
	v_mov_b64_e32 v[2:3], 0
	s_addc_u32 s96, s93, 0
	s_mov_b32 s97, -2

.Lzskip_gdn:
	v_mov_b64_e32 v[20:21], 0
	v_mov_b64_e32 v[22:23], 0
	v_mov_b64_e32 v[24:25], 0
	v_mov_b64_e32 v[26:27], 0
	v_mov_b64_e32 v[28:29], 0
	v_mov_b64_e32 v[30:31], 0
	v_mov_b64_e32 v[32:33], 0
	v_mov_b64_e32 v[34:35], 0
	v_mov_b64_e32 v[36:37], 0
	v_mov_b64_e32 v[38:39], 0
	v_mov_b64_e32 v[40:41], 0
	v_mov_b64_e32 v[42:43], 0
	v_mov_b64_e32 v[44:45], 0
	v_mov_b64_e32 v[46:47], 0
	v_mov_b64_e32 v[48:49], 0
	v_mov_b64_e32 v[50:51], 0
	v_mov_b64_e32 v[52:53], 0
	v_mov_b64_e32 v[54:55], 0
	v_mov_b64_e32 v[56:57], 0
	v_mov_b64_e32 v[58:59], 0
	v_mov_b64_e32 v[60:61], 0
	v_mov_b64_e32 v[62:63], 0
	v_mov_b64_e32 v[64:65], 0
	v_mov_b64_e32 v[66:67], 0
	v_mov_b64_e32 v[68:69], 0
	v_mov_b64_e32 v[70:71], 0
	v_mov_b64_e32 v[72:73], 0
	v_mov_b64_e32 v[74:75], 0
	v_mov_b64_e32 v[76:77], 0
	v_mov_b64_e32 v[78:79], 0
	v_mov_b64_e32 v[80:81], 0
	v_mov_b64_e32 v[82:83], 0
	v_mov_b64_e32 v[84:85], 0
	v_mov_b64_e32 v[86:87], 0
	v_mov_b64_e32 v[88:89], 0
	v_mov_b64_e32 v[90:91], 0
	v_mov_b64_e32 v[92:93], 0
	v_mov_b64_e32 v[94:95], 0
	v_mov_b64_e32 v[96:97], 0
	v_mov_b64_e32 v[98:99], 0
	v_mov_b64_e32 v[100:101], 0
	s_branch .LBB0_183
	s_nop 0
	s_nop 0
	s_nop 0
	s_nop 0
	s_nop 0
	s_nop 0

.LBB0_177:
	s_add_i32 s27, s27, 1
	v_mov_b64_e32 v[4:5], 0
	s_mul_i32 s38, s27, s97
	v_mov_b64_e32 v[6:7], 0
	s_mul_hi_u32 s39, s27, s12
	v_mov_b64_e32 v[8:9], 0
	s_add_i32 s39, s39, s38
	v_mov_b64_e32 v[10:11], 0
	s_mul_i32 s38, s27, s12
	v_mov_b64_e32 v[12:13], 0
	s_add_u32 s38, s38, s28
	v_mov_b64_e32 v[14:15], 0
	s_addc_u32 s39, s39, s98
	v_mov_b64_e32 v[16:17], 0
	s_waitcnt lgkmcnt(0)
	v_mov_b64_e32 v[18:19], 0
	v_mov_b64_e32 v[2:3], 0x200
	v_cmp_lt_i64_e64 s[40:41], s[38:39], v[2:3]
	v_mov_b64_e32 v[2:3], 0x1ff
	v_cmp_gt_i64_e32 vcc, s[38:39], v[2:3]
	s_cbranch_vccnz .Lzskip_gdn
	s_ashr_i32 s2, s38, 31
	s_lshr_b32 s2, s2, 29
	s_add_i32 s2, s38, s2
	s_and_b32 s6, s2, -8
	s_sub_i32 s6, s38, s6
	s_cmp_gt_i32 s6, -1
	s_mov_b64 s[38:39], -1
	s_cbranch_scc0 .LBB0_180
	s_lshl_b32 s88, s6, 6
	s_mov_b64 s[38:39], 0

.LBB0_182:
	s_ashr_i32 s2, s2, 3
	v_mov_b64_e32 v[20:21], 0
	s_add_i32 s2, s88, s2
	v_mov_b64_e32 v[22:23], 0
	s_ashr_i32 s6, s2, 31
	v_mov_b64_e32 v[24:25], 0
	s_lshr_b32 s6, s6, 27
	v_mov_b64_e32 v[26:27], 0
	s_add_i32 s6, s2, s6
	v_mov_b64_e32 v[28:29], 0
	s_ashr_i32 s38, s6, 5
	v_mov_b64_e32 v[30:31], 0
	s_lshl_b32 s38, s38, 3
	v_mov_b64_e32 v[32:33], 0
	s_sub_i32 s39, 0x80, s38
	v_mov_b64_e32 v[34:35], 0
	s_min_i32 s39, s39, 8
	v_mov_b64_e32 v[36:37], 0
	s_abs_i32 s68, s39
	v_mov_b64_e32 v[38:39], 0
	v_cvt_f32_u32_e32 v2, s68
	v_mov_b64_e32 v[40:41], 0
	s_sub_i32 s70, 0, s68
	v_mov_b64_e32 v[42:43], 0
	s_andn2_b32 s6, s6, 31
	v_mov_b64_e32 v[44:45], 0
	s_sub_i32 s6, s2, s6
	v_mov_b64_e32 v[46:47], 0
	v_rcp_iflag_f32_e32 v2, v2
	v_mov_b64_e32 v[48:49], 0
	s_abs_i32 s2, s6
	v_mov_b64_e32 v[50:51], 0
	s_xor_b32 s69, s6, s39
	v_mov_b64_e32 v[52:53], 0
	s_ashr_i32 s69, s69, 31
	v_mov_b64_e32 v[54:55], 0
	v_mul_f32_e32 v2, 0x4f7ffffe, v2
	v_mov_b64_e32 v[56:57], 0
	v_cvt_u32_f32_e32 v2, v2
	v_mov_b64_e32 v[58:59], 0
	s_nop 0
	v_mov_b64_e32 v[60:61], 0
	v_readfirstlane_b32 s71, v2
	v_mov_b64_e32 v[62:63], 0
	s_mul_i32 s70, s70, s71
	v_mov_b64_e32 v[64:65], 0
	s_mul_hi_u32 s70, s71, s70
	v_mov_b64_e32 v[66:67], 0
	s_add_i32 s71, s71, s70
	v_mov_b64_e32 v[68:69], 0
	s_mul_hi_u32 s70, s2, s71
	v_mov_b64_e32 v[70:71], 0
	s_mul_i32 s71, s70, s68
	v_mov_b64_e32 v[72:73], 0
	s_sub_i32 s2, s2, s71
	v_mov_b64_e32 v[74:75], 0
	s_add_i32 s72, s70, 1
	v_mov_b64_e32 v[76:77], 0
	s_sub_i32 s71, s2, s68
	v_mov_b64_e32 v[78:79], 0
	s_cmp_ge_u32 s2, s68
	v_mov_b64_e32 v[80:81], 0
	s_cselect_b32 s70, s72, s70
	v_mov_b64_e32 v[82:83], 0
	s_cselect_b32 s2, s71, s2
	v_mov_b64_e32 v[84:85], 0
	s_add_i32 s71, s70, 1
	v_mov_b64_e32 v[86:87], 0
	s_cmp_ge_u32 s2, s68
	v_mov_b64_e32 v[88:89], 0
	s_cselect_b32 s2, s71, s70
	v_mov_b64_e32 v[90:91], 0
	s_xor_b32 s2, s2, s69
	v_mov_b64_e32 v[92:93], 0
	s_sub_i32 s2, s2, s69
	v_mov_b64_e32 v[94:95], 0
	s_mul_i32 s39, s2, s39
	v_mov_b64_e32 v[96:97], 0
	s_sub_i32 s6, s6, s39
	v_mov_b64_e32 v[98:99], 0
	s_add_i32 s6, s38, s6
	v_mov_b64_e32 v[100:101], 0
.LBB0_183:
	v_cndmask_b32_e64 v2, 0, 1, s[40:41]
	v_mov_b64_e32 v[102:103], 0
	v_cmp_ne_u32_e64 s[38:39], 1, v2
	v_mov_b64_e32 v[104:105], 0
	s_andn2_b64 vcc, exec, s[40:41]
	v_mov_b64_e32 v[114:115], 0
	s_mov_b64 s[88:89], s[94:95]
	v_mov_b64_e32 v[116:117], 0
	s_cbranch_vccnz .LBB0_185
	s_mul_i32 s41, s17, s6
	s_mul_hi_i32 s40, s17, s6
	s_add_u32 s88, s50, s41
	s_addc_u32 s89, s51, s40

.LBB0_187:
	s_add_u32 s40, s94, 0x80
	v_mov_b64_e32 v[118:119], 0
	s_addc_u32 s41, s95, 0
	v_mov_b64_e32 v[120:121], 0
	s_add_u32 s94, s92, 0x100
	v_mov_b64_e32 v[130:131], 0
	v_mov_b64_e32 v[2:3], 0
	v_mov_b64_e32 v[132:133], 0
	v_mov_b64_e32 v[134:135], 0
	v_mov_b64_e32 v[136:137], 0
	v_mov_b64_e32 v[138:139], 0
	v_mov_b64_e32 v[140:141], 0
	v_mov_b64_e32 v[142:143], 0
	v_mov_b64_e32 v[144:145], 0
	s_addc_u32 s95, s93, 0
	s_mov_b32 s92, 0

.Lzskip_gup:
	v_mov_b64_e32 v[30:31], 0
	v_mov_b64_e32 v[32:33], 0
	v_mov_b64_e32 v[34:35], 0
	v_mov_b64_e32 v[36:37], 0
	v_mov_b64_e32 v[38:39], 0
	v_mov_b64_e32 v[40:41], 0
	v_mov_b64_e32 v[42:43], 0
	v_mov_b64_e32 v[44:45], 0
	v_mov_b64_e32 v[46:47], 0
	v_mov_b64_e32 v[48:49], 0
	v_mov_b64_e32 v[50:51], 0
	v_mov_b64_e32 v[52:53], 0
	v_mov_b64_e32 v[54:55], 0
	v_mov_b64_e32 v[56:57], 0
	v_mov_b64_e32 v[58:59], 0
	v_mov_b64_e32 v[60:61], 0
	v_mov_b64_e32 v[62:63], 0
	v_mov_b64_e32 v[64:65], 0
	v_mov_b64_e32 v[66:67], 0
	v_mov_b64_e32 v[68:69], 0
	v_mov_b64_e32 v[70:71], 0
	v_mov_b64_e32 v[72:73], 0
	v_mov_b64_e32 v[86:87], 0
	v_mov_b64_e32 v[88:89], 0
	v_mov_b64_e32 v[90:91], 0
	v_mov_b64_e32 v[92:93], 0
	v_mov_b64_e32 v[94:95], 0
	v_mov_b64_e32 v[96:97], 0
	v_mov_b64_e32 v[98:99], 0
	v_mov_b64_e32 v[100:101], 0
	v_mov_b64_e32 v[102:103], 0
	v_mov_b64_e32 v[104:105], 0
	v_mov_b64_e32 v[106:107], 0
	v_mov_b64_e32 v[108:109], 0
	v_mov_b64_e32 v[110:111], 0
	v_mov_b64_e32 v[112:113], 0
	v_mov_b64_e32 v[114:115], 0
	v_mov_b64_e32 v[116:117], 0
	v_mov_b64_e32 v[118:119], 0
	v_mov_b64_e32 v[120:121], 0
	v_mov_b64_e32 v[122:123], 0
	v_mov_b64_e32 v[124:125], 0
	v_mov_b64_e32 v[126:127], 0
	v_mov_b64_e32 v[128:129], 0
	v_mov_b64_e32 v[130:131], 0
	v_mov_b64_e32 v[132:133], 0
	v_mov_b64_e32 v[134:135], 0
	v_mov_b64_e32 v[136:137], 0
	v_mov_b64_e32 v[138:139], 0
	v_mov_b64_e32 v[140:141], 0
	s_branch .LBB0_242
	s_nop 0
	s_nop 0
	s_nop 0
	s_nop 0
	s_nop 0
	s_nop 0
	s_nop 0
	s_nop 0
	s_nop 0
	s_nop 0
	s_nop 0
	s_nop 0
	s_nop 0

.LBB0_240:
	s_add_i32 s23, s23, 1
	v_mov_b64_e32 v[4:5], 0
	s_mul_i32 s2, s23, s21
	v_mov_b64_e32 v[6:7], 0
	s_mul_hi_u32 s6, s23, s12
	v_mov_b64_e32 v[8:9], 0
	s_add_i32 s6, s6, s2
	v_mov_b64_e32 v[10:11], 0
	s_mul_i32 s2, s23, s12
	v_mov_b64_e32 v[12:13], 0
	s_add_u32 s90, s2, s28
	v_mov_b64_e32 v[18:19], 0
	s_addc_u32 s91, s6, s22
	v_mov_b64_e32 v[20:21], 0
	v_mov_b64_e32 v[2:3], 0xb00
	v_cmp_lt_i64_e64 s[38:39], s[90:91], v[2:3]
	v_mov_b64_e32 v[2:3], 0xaff
	v_cmp_gt_i64_e32 vcc, s[90:91], v[2:3]
	s_cbranch_vccnz .Lzskip_gup
	s_ashr_i32 s2, s90, 31
	v_mov_b64_e32 v[30:31], 0
	s_lshr_b32 s2, s2, 29
	v_mov_b64_e32 v[32:33], 0
	s_add_i32 s2, s90, s2
	v_mov_b64_e32 v[34:35], 0
	s_ashr_i32 s6, s2, 3
	v_mov_b64_e32 v[36:37], 0
	s_and_b32 s2, s2, -8
	v_mov_b64_e32 v[38:39], 0
	s_sub_i32 s2, s90, s2
	v_mov_b64_e32 v[40:41], 0
	s_cmp_lt_i32 s2, 0
	v_mov_b64_e32 v[42:43], 0
	s_movk_i32 s41, 0x161
	v_mov_b64_e32 v[44:45], 0
	s_cselect_b32 s41, s41, 0x160
	v_mov_b64_e32 v[46:47], 0
	s_mul_i32 s2, s2, s41
	v_mov_b64_e32 v[48:49], 0
	s_add_i32 s2, s2, s6
	v_mov_b64_e32 v[50:51], 0
	s_mul_hi_i32 s6, s2, 0x2e8ba2e9
	v_mov_b64_e32 v[52:53], 0
	s_lshr_b32 s41, s6, 31
	v_mov_b64_e32 v[54:55], 0
	s_ashr_i32 s6, s6, 5
	v_mov_b64_e32 v[56:57], 0
	s_add_i32 s6, s6, s41
	v_mov_b64_e32 v[58:59], 0
	s_lshl_b32 s41, s6, 3
	v_mov_b64_e32 v[60:61], 0
	s_sub_i32 s48, 0x80, s41
	v_mov_b64_e32 v[62:63], 0
	s_min_i32 s48, s48, 8
	v_mov_b64_e32 v[64:65], 0
	s_abs_i32 s70, s48
	v_mov_b64_e32 v[66:67], 0
	v_cvt_f32_u32_e32 v0, s70
	v_mov_b64_e32 v[68:69], 0
	s_sub_i32 s72, 0, s70
	v_mov_b64_e32 v[70:71], 0
	s_mulk_i32 s6, 0xb0
	v_mov_b64_e32 v[72:73], 0
	s_sub_i32 s2, s2, s6
	v_mov_b64_e32 v[86:87], 0
	v_rcp_iflag_f32_e32 v0, v0
	v_mov_b64_e32 v[88:89], 0
	s_abs_i32 s6, s2
	v_mov_b64_e32 v[90:91], 0
	s_xor_b32 s71, s2, s48
	v_mov_b64_e32 v[92:93], 0
	s_ashr_i32 s71, s71, 31
	v_mov_b64_e32 v[94:95], 0
	v_mul_f32_e32 v0, 0x4f7ffffe, v0
	v_mov_b64_e32 v[96:97], 0
	v_cvt_u32_f32_e32 v0, v0
	v_mov_b64_e32 v[98:99], 0
	s_nop 0
	v_mov_b64_e32 v[100:101], 0
	v_readfirstlane_b32 s73, v0
	v_mov_b64_e32 v[102:103], 0
	s_mul_i32 s72, s72, s73
	v_mov_b64_e32 v[104:105], 0
	s_mul_hi_u32 s72, s73, s72
	v_mov_b64_e32 v[106:107], 0
	s_add_i32 s73, s73, s72
	v_mov_b64_e32 v[108:109], 0
	s_mul_hi_u32 s72, s6, s73
	v_mov_b64_e32 v[110:111], 0
	s_mul_i32 s73, s72, s70
	v_mov_b64_e32 v[112:113], 0
	s_sub_i32 s6, s6, s73
	v_mov_b64_e32 v[114:115], 0
	s_add_i32 s77, s72, 1
	v_mov_b64_e32 v[116:117], 0
	s_sub_i32 s73, s6, s70
	v_mov_b64_e32 v[118:119], 0
	s_cmp_ge_u32 s6, s70
	v_mov_b64_e32 v[120:121], 0
	s_cselect_b32 s72, s77, s72
	v_mov_b64_e32 v[122:123], 0
	s_cselect_b32 s6, s73, s6
	v_mov_b64_e32 v[124:125], 0
	s_add_i32 s73, s72, 1
	v_mov_b64_e32 v[126:127], 0
	s_cmp_ge_u32 s6, s70
	v_mov_b64_e32 v[128:129], 0
	s_cselect_b32 s6, s73, s72
	v_mov_b64_e32 v[130:131], 0
	s_xor_b32 s6, s6, s71
	v_mov_b64_e32 v[132:133], 0
	s_sub_i32 s88, s6, s71
	v_mov_b64_e32 v[134:135], 0
	s_mul_i32 s6, s88, s48
	v_mov_b64_e32 v[136:137], 0
	s_sub_i32 s2, s2, s6
	v_mov_b64_e32 v[138:139], 0
	s_add_i32 s94, s41, s2
	v_mov_b64_e32 v[140:141], 0
.LBB0_242:
	s_ashr_i32 s95, s94, 31
	v_mov_b64_e32 v[142:143], 0
	s_lshl_b64 s[70:71], s[94:95], 19
	v_mov_b64_e32 v[144:145], 0
	s_add_u32 s90, s36, s70
	v_mov_b64_e32 v[146:147], 0
	s_addc_u32 s91, s37, s71
	v_mov_b64_e32 v[148:149], 0
	s_and_b64 s[70:71], s[38:39], exec
	v_mov_b64_e32 v[150:151], 0
	s_cselect_b32 s2, s91, s43
	v_mov_b64_e32 v[152:153], 0
	s_cselect_b32 s6, s90, s42
	s_ashr_i32 s89, s88, 31
	s_lshl_b64 s[70:71], s[88:89], 19
	s_add_u32 s96, s50, s70
	s_addc_u32 s97, s51, s71
	s_and_b64 s[70:71], s[38:39], exec
	s_cselect_b32 s41, s97, s93
	s_cselect_b32 s48, s96, s92
	s_add_u32 s42, s42, 0x40080
	s_addc_u32 s43, s43, 0
	s_add_u32 s77, s92, 0x100
	v_mov_b64_e32 v[2:3], 0
	s_addc_u32 s89, s93, 0
	s_mov_b32 s95, -2
	s_waitcnt lgkmcnt(0)
